# prep phase: workgroups that run a modulation-GEMV item no longer also run weight-transpose tiles (static split 192 / 320 workgroups)
# speedup vs baseline: 1.1743x; 1.0094x over previous
; DI void ph_prep(const Params& p, unsigned char* smem, int bid, int nb) {
;     ...
;   for (int it = bid; it < total; it += nb) {
;     if (it >= n_mod_items && it < n_mod_items + WT_TILES) {
;       wt_tile(p, 0, it - n_mod_items, smem, tid);
;     } else if (it < n_mod_items) {
.LBB0_19:
	v_readlane_b32 s1, v253, 43
	s_cmpk_eq_i32 s1, 0x200
	s_cbranch_scc0 .Lpp_std
	v_readlane_b32 s10, v253, 42
	s_nop 0
	s_cmpk_lt_u32 s10, 0xc0
	s_movk_i32 s1, 0x140
	s_cselect_b32 s1, 0x1000, s1
.Lpp_std:
	s_add_i32 s0, s0, s1
	s_cmpk_lt_i32 s0, 0x621
	s_cbranch_scc0 .LBB0_61
